# sc1 nt (drop from L2) instead of nt on the d_out stores of the final rmsnorm
# baseline (speedup 1.0000x reference)
; __device__ __forceinline__ float bf_lo(unsigned w) { return __uint_as_float(w << 16); }
; __device__ __forceinline__ float bf_hi(unsigned w) { return __uint_as_float(w & 0xffff0000u); }
; __global__ void __launch_bounds__(512, 2) mega(Args A) {
;     ...
;         for (int m = m0; m < m1; m += 4 * ms) {
;             float rinv[4]; unsigned long long w[4][4];
; #pragma unroll
;             for (int q = 0; q < 4; ++q) { const int mq = (m + q * ms < m1) ? m + q * ms : m; rinv[q] = row_rinv(pr, mq);
;                 const unsigned long long* hr = (const unsigned long long*)(HB0 + (size_t)mq * DM) + lane;
; #pragma unroll
;                 for (int j = 0; j < 4; ++j) w[q][j] = hr[64 * j]; }
; #pragma unroll
;             for (int q = 0; q < 4; ++q) if (m + q * ms < m1) { f32x4* orow = (f32x4*)(A.out + (size_t)(m + q * ms) * DM) + lane;
; #pragma unroll
;                 for (int j = 0; j < 4; ++j) { const unsigned lo = (unsigned)w[q][j], hi = (unsigned)(w[q][j] >> 32);
;                     const f32x4 v = {bf_lo(lo), bf_hi(lo), bf_lo(hi), bf_hi(hi)}; orow[64 * j] = v * rinv[q] * gv[j]; } }
.LBB0_626:
	v_ashrrev_i32_e32 v65, 31, v64
	v_lshlrev_b64 v[18:19], 6, v[64:65]
	v_lshl_add_u64 v[18:19], s[80:81], 0, v[18:19]
	global_load_dwordx4 v[102:105], v[18:19], off offset:32 nt
	global_load_dwordx4 v[106:109], v[18:19], off offset:48 nt
	global_load_dwordx4 v[110:113], v[18:19], off nt
	global_load_dwordx4 v[114:117], v[18:19], off offset:16 nt
	v_add_u32_e32 v90, s8, v64
	v_cmp_gt_i32_e64 s[2:3], s9, v90
	v_lshlrev_b64 v[18:19], 11, v[64:65]
	v_lshl_add_u64 v[18:19], v[66:67], 0, v[18:19]
	v_cndmask_b32_e64 v16, v64, v90, s[2:3]
	v_ashrrev_i32_e32 v17, 31, v16
	global_load_dwordx2 v[118:119], v[18:19], off offset:1536 nt
	global_load_dwordx2 v[120:121], v[18:19], off offset:1024 nt
	global_load_dwordx2 v[122:123], v[18:19], off offset:512 nt
	global_load_dwordx2 v[124:125], v[18:19], off nt
	v_lshlrev_b64 v[18:19], 6, v[16:17]
	v_lshlrev_b64 v[16:17], 11, v[16:17]
	v_add_u32_e32 v86, s11, v64
	v_lshl_add_u64 v[18:19], s[80:81], 0, v[18:19]
	v_lshl_add_u64 v[16:17], v[66:67], 0, v[16:17]
	v_cmp_gt_i32_e64 s[0:1], s9, v86
	global_load_dwordx4 v[48:51], v[18:19], off offset:48 nt
	global_load_dwordx4 v[52:55], v[18:19], off offset:32 nt
	global_load_dwordx4 v[56:59], v[18:19], off offset:16 nt
	global_load_dwordx4 v[60:63], v[18:19], off nt
	global_load_dwordx2 v[98:99], v[16:17], off nt
	global_load_dwordx2 v[96:97], v[16:17], off offset:512 nt
	global_load_dwordx2 v[94:95], v[16:17], off offset:1024 nt
	global_load_dwordx2 v[92:93], v[16:17], off offset:1536 nt
	v_cndmask_b32_e64 v16, v64, v86, s[0:1]
	v_add_u32_e32 v76, s12, v64
	v_ashrrev_i32_e32 v17, 31, v16
	v_cmp_gt_i32_e32 vcc, s9, v76
	v_lshlrev_b64 v[18:19], 6, v[16:17]
	v_lshlrev_b64 v[16:17], 11, v[16:17]
	v_cndmask_b32_e32 v70, v64, v76, vcc
	v_lshl_add_u64 v[18:19], s[80:81], 0, v[18:19]
	v_lshl_add_u64 v[16:17], v[66:67], 0, v[16:17]
	v_ashrrev_i32_e32 v71, 31, v70
	global_load_dwordx4 v[32:35], v[18:19], off offset:48 nt
	global_load_dwordx4 v[36:39], v[18:19], off offset:32 nt
	global_load_dwordx4 v[40:43], v[18:19], off offset:16 nt
	global_load_dwordx4 v[44:47], v[18:19], off nt
	global_load_dwordx2 v[88:89], v[16:17], off nt
	global_load_dwordx2 v[84:85], v[16:17], off offset:512 nt
	global_load_dwordx2 v[82:83], v[16:17], off offset:1024 nt
	global_load_dwordx2 v[80:81], v[16:17], off offset:1536 nt
	v_lshlrev_b64 v[16:17], 6, v[70:71]
	v_lshlrev_b64 v[70:71], 11, v[70:71]
	v_lshl_add_u64 v[72:73], s[80:81], 0, v[16:17]
	v_lshl_add_u64 v[126:127], v[66:67], 0, v[70:71]
	global_load_dwordx4 v[16:19], v[72:73], off offset:48 nt
	global_load_dwordx4 v[20:23], v[72:73], off offset:32 nt
	global_load_dwordx4 v[24:27], v[72:73], off offset:16 nt
	global_load_dwordx4 v[28:31], v[72:73], off nt
	global_load_dwordx2 v[78:79], v[126:127], off nt
	global_load_dwordx2 v[74:75], v[126:127], off offset:512 nt
	s_nop 0
	global_load_dwordx2 v[72:73], v[126:127], off offset:1024 nt
	global_load_dwordx2 v[70:71], v[126:127], off offset:1536 nt
	v_lshlrev_b64 v[126:127], 12, v[64:65]
	v_lshl_add_u64 v[126:127], v[68:69], 0, v[126:127]
	s_waitcnt vmcnt(0)
	v_pk_add_f32 v[104:105], v[104:105], v[108:109]
	v_pk_add_f32 v[102:103], v[102:103], v[106:107]
	v_pk_add_f32 v[112:113], v[112:113], v[116:117]
	v_pk_add_f32 v[110:111], v[110:111], v[114:115]
	v_pk_add_f32 v[104:105], v[112:113], v[104:105]
	v_pk_add_f32 v[102:103], v[110:111], v[102:103]
	v_lshlrev_b32_e32 v112, 16, v120
	v_pk_mov_b32 v[110:111], v[102:103], v[104:105] op_sel:[1,0]
	v_mov_b32_e32 v103, v105
	v_pk_add_f32 v[102:103], v[110:111], v[102:103]
	v_lshlrev_b32_e32 v106, 16, v124
	v_add_f32_e32 v65, v102, v103
	v_fmamk_f32 v65, v65, 0x3a800000, v100
	v_rsq_f32_e32 v110, v65
	v_and_b32_e32 v107, 0xffff0000, v124
	v_lshlrev_b32_e32 v108, 16, v125
	v_and_b32_e32 v109, 0xffff0000, v125
	v_lshlrev_b32_e32 v114, 16, v122
	v_and_b32_e32 v115, 0xffff0000, v122
	v_lshlrev_b32_e32 v116, 16, v123
	v_and_b32_e32 v117, 0xffff0000, v123
	v_pk_mul_f32 v[102:103], v[110:111], v[106:107] op_sel_hi:[0,1]
	v_pk_mul_f32 v[104:105], v[110:111], v[108:109] op_sel_hi:[0,1]
	v_and_b32_e32 v113, 0xffff0000, v120
	v_lshlrev_b32_e32 v120, 16, v121
	v_pk_mul_f32 v[106:107], v[110:111], v[114:115] op_sel_hi:[0,1]
	v_pk_mul_f32 v[108:109], v[110:111], v[116:117] op_sel_hi:[0,1]
	v_pk_mul_f32 v[104:105], v[2:3], v[104:105]
	v_pk_mul_f32 v[102:103], v[0:1], v[102:103]
	v_and_b32_e32 v121, 0xffff0000, v121
	v_pk_mul_f32 v[108:109], v[6:7], v[108:109]
	v_pk_mul_f32 v[106:107], v[4:5], v[106:107]
	global_store_dwordx4 v[126:127], v[102:105], off sc1 nt
	global_store_dwordx4 v[126:127], v[106:109], off offset:1024 sc1 nt
	s_nop 0
	v_pk_mul_f32 v[102:103], v[110:111], v[112:113] op_sel_hi:[0,1]
	v_pk_mul_f32 v[104:105], v[110:111], v[120:121] op_sel_hi:[0,1]
	v_pk_mul_f32 v[104:105], v[10:11], v[104:105]
	v_pk_mul_f32 v[102:103], v[8:9], v[102:103]
	global_store_dwordx4 v[126:127], v[102:105], off offset:2048 sc1 nt
	s_nop 1
	v_lshlrev_b32_e32 v102, 16, v118
	v_and_b32_e32 v103, 0xffff0000, v118
	v_lshlrev_b32_e32 v104, 16, v119
	v_and_b32_e32 v105, 0xffff0000, v119
	v_pk_mul_f32 v[102:103], v[110:111], v[102:103] op_sel_hi:[0,1]
	v_pk_mul_f32 v[104:105], v[110:111], v[104:105] op_sel_hi:[0,1]
	v_pk_mul_f32 v[104:105], v[14:15], v[104:105]
	v_pk_mul_f32 v[102:103], v[12:13], v[102:103]
	global_store_dwordx4 v[126:127], v[102:105], off offset:3072 sc1 nt
	s_and_saveexec_b64 s[6:7], s[2:3]
	s_cbranch_execnz .LBB0_629
	s_or_b64 exec, exec, s[6:7]
	s_and_saveexec_b64 s[2:3], s[0:1]
	s_cbranch_execnz .LBB0_630

; __device__ __forceinline__ float bf_lo(unsigned w) { return __uint_as_float(w << 16); }
; __device__ __forceinline__ float bf_hi(unsigned w) { return __uint_as_float(w & 0xffff0000u); }
; __device__ __forceinline__ float row_rinv(const float* part, int row) {
;     const f32x4* p = (const f32x4*)(part + (size_t)row * 16);
;     const f32x4 s = (p[0] + p[1]) + (p[2] + p[3]);
;     return __builtin_amdgcn_rsqf(((s[0] + s[1]) + (s[2] + s[3])) * (1.0f / 1024.0f) + EPS);
; __global__ void __launch_bounds__(512, 2) mega(Args A) {
;     ...
;             for (int q = 0; q < 4; ++q) if (m + q * ms < m1) { f32x4* orow = (f32x4*)(A.out + (size_t)(m + q * ms) * DM) + lane;
; #pragma unroll
;                 for (int j = 0; j < 4; ++j) { const unsigned lo = (unsigned)w[q][j], hi = (unsigned)(w[q][j] >> 32);
;                     const f32x4 v = {bf_lo(lo), bf_hi(lo), bf_lo(hi), bf_hi(hi)}; orow[64 * j] = v * rinv[q] * gv[j]; } }
.LBB0_629:
	v_pk_add_f32 v[58:59], v[62:63], v[58:59]
	v_pk_add_f32 v[56:57], v[60:61], v[56:57]
	v_pk_add_f32 v[48:49], v[52:53], v[48:49]
	v_pk_add_f32 v[50:51], v[54:55], v[50:51]
	v_pk_add_f32 v[48:49], v[56:57], v[48:49]
	v_pk_add_f32 v[50:51], v[58:59], v[50:51]
	v_ashrrev_i32_e32 v91, 31, v90
	v_pk_mov_b32 v[52:53], v[48:49], v[50:51] op_sel:[1,0]
	v_mov_b32_e32 v49, v51
	v_pk_add_f32 v[48:49], v[52:53], v[48:49]
	v_lshlrev_b32_e32 v50, 16, v99
	v_add_f32_e32 v48, v48, v49
	v_fmamk_f32 v48, v48, 0x3a800000, v100
	v_rsq_f32_e32 v52, v48
	v_lshlrev_b64 v[48:49], 12, v[90:91]
	v_lshl_add_u64 v[54:55], v[68:69], 0, v[48:49]
	v_lshlrev_b32_e32 v48, 16, v98
	v_and_b32_e32 v49, 0xffff0000, v98
	v_and_b32_e32 v51, 0xffff0000, v99
	v_pk_mul_f32 v[48:49], v[52:53], v[48:49] op_sel_hi:[0,1]
	v_pk_mul_f32 v[50:51], v[52:53], v[50:51] op_sel_hi:[0,1]
	v_pk_mul_f32 v[50:51], v[2:3], v[50:51]
	v_pk_mul_f32 v[48:49], v[0:1], v[48:49]
	global_store_dwordx4 v[54:55], v[48:51], off sc1 nt
	s_nop 1
	v_lshlrev_b32_e32 v48, 16, v96
	v_and_b32_e32 v49, 0xffff0000, v96
	v_lshlrev_b32_e32 v50, 16, v97
	v_and_b32_e32 v51, 0xffff0000, v97
	v_pk_mul_f32 v[48:49], v[52:53], v[48:49] op_sel_hi:[0,1]
	v_pk_mul_f32 v[50:51], v[52:53], v[50:51] op_sel_hi:[0,1]
	v_pk_mul_f32 v[50:51], v[6:7], v[50:51]
	v_pk_mul_f32 v[48:49], v[4:5], v[48:49]
	global_store_dwordx4 v[54:55], v[48:51], off offset:1024 sc1 nt
	s_nop 1
	v_lshlrev_b32_e32 v48, 16, v94
	v_and_b32_e32 v49, 0xffff0000, v94
	v_lshlrev_b32_e32 v50, 16, v95
	v_and_b32_e32 v51, 0xffff0000, v95
	v_pk_mul_f32 v[48:49], v[52:53], v[48:49] op_sel_hi:[0,1]
	v_pk_mul_f32 v[50:51], v[52:53], v[50:51] op_sel_hi:[0,1]
	v_pk_mul_f32 v[50:51], v[10:11], v[50:51]
	v_pk_mul_f32 v[48:49], v[8:9], v[48:49]
	global_store_dwordx4 v[54:55], v[48:51], off offset:2048 sc1 nt
	s_nop 1
	v_lshlrev_b32_e32 v48, 16, v92
	v_and_b32_e32 v49, 0xffff0000, v92
	v_lshlrev_b32_e32 v50, 16, v93
	v_and_b32_e32 v51, 0xffff0000, v93
	v_pk_mul_f32 v[48:49], v[52:53], v[48:49] op_sel_hi:[0,1]
	v_pk_mul_f32 v[50:51], v[52:53], v[50:51] op_sel_hi:[0,1]
	v_pk_mul_f32 v[50:51], v[14:15], v[50:51]
	v_pk_mul_f32 v[48:49], v[12:13], v[48:49]
	global_store_dwordx4 v[54:55], v[48:51], off offset:3072 sc1 nt
	s_or_b64 exec, exec, s[6:7]
	s_and_saveexec_b64 s[2:3], s[0:1]
	s_cbranch_execz .LBB0_628
.LBB0_630:
	v_pk_add_f32 v[42:43], v[46:47], v[42:43]
	v_pk_add_f32 v[40:41], v[44:45], v[40:41]
	v_pk_add_f32 v[32:33], v[36:37], v[32:33]
	v_pk_add_f32 v[34:35], v[38:39], v[34:35]
	v_pk_add_f32 v[32:33], v[40:41], v[32:33]
	v_pk_add_f32 v[34:35], v[42:43], v[34:35]
	v_add_f32_e32 v32, v32, v33
	v_add_f32_e32 v33, v34, v35
	v_add_f32_e32 v32, v32, v33
	v_fmamk_f32 v32, v32, 0x3a800000, v100
	v_rsq_f32_e32 v36, v32
	v_ashrrev_i32_e32 v87, 31, v86
	v_lshlrev_b64 v[32:33], 12, v[86:87]
	v_lshl_add_u64 v[38:39], v[68:69], 0, v[32:33]
	v_lshlrev_b32_e32 v32, 16, v88
	v_and_b32_e32 v33, 0xffff0000, v88
	v_lshlrev_b32_e32 v34, 16, v89
	v_and_b32_e32 v35, 0xffff0000, v89
	v_pk_mul_f32 v[32:33], v[36:37], v[32:33] op_sel_hi:[0,1]
	v_pk_mul_f32 v[34:35], v[36:37], v[34:35] op_sel_hi:[0,1]
	v_pk_mul_f32 v[34:35], v[2:3], v[34:35]
	v_pk_mul_f32 v[32:33], v[0:1], v[32:33]
	global_store_dwordx4 v[38:39], v[32:35], off sc1 nt
	s_nop 1
	v_lshlrev_b32_e32 v32, 16, v84
	v_and_b32_e32 v33, 0xffff0000, v84
	v_lshlrev_b32_e32 v34, 16, v85
	v_and_b32_e32 v35, 0xffff0000, v85
	v_pk_mul_f32 v[32:33], v[36:37], v[32:33] op_sel_hi:[0,1]
	v_pk_mul_f32 v[34:35], v[36:37], v[34:35] op_sel_hi:[0,1]
	v_pk_mul_f32 v[34:35], v[6:7], v[34:35]
	v_pk_mul_f32 v[32:33], v[4:5], v[32:33]
	global_store_dwordx4 v[38:39], v[32:35], off offset:1024 sc1 nt
	s_nop 1
	v_lshlrev_b32_e32 v32, 16, v82
	v_and_b32_e32 v33, 0xffff0000, v82
	v_lshlrev_b32_e32 v34, 16, v83
	v_and_b32_e32 v35, 0xffff0000, v83
	v_pk_mul_f32 v[32:33], v[36:37], v[32:33] op_sel_hi:[0,1]
	v_pk_mul_f32 v[34:35], v[36:37], v[34:35] op_sel_hi:[0,1]
	v_pk_mul_f32 v[34:35], v[10:11], v[34:35]
	v_pk_mul_f32 v[32:33], v[8:9], v[32:33]
	global_store_dwordx4 v[38:39], v[32:35], off offset:2048 sc1 nt
	s_nop 1
	v_lshlrev_b32_e32 v32, 16, v80
	v_and_b32_e32 v33, 0xffff0000, v80
	v_lshlrev_b32_e32 v34, 16, v81
	v_and_b32_e32 v35, 0xffff0000, v81
	v_pk_mul_f32 v[32:33], v[36:37], v[32:33] op_sel_hi:[0,1]
	v_pk_mul_f32 v[34:35], v[36:37], v[34:35] op_sel_hi:[0,1]
	v_pk_mul_f32 v[34:35], v[14:15], v[34:35]
	v_pk_mul_f32 v[32:33], v[12:13], v[32:33]
	global_store_dwordx4 v[38:39], v[32:35], off offset:3072 sc1 nt
	s_or_b64 exec, exec, s[2:3]
	s_and_saveexec_b64 s[0:1], vcc
	s_cbranch_execz .LBB0_625
.LBB0_631:
	v_pk_add_f32 v[26:27], v[30:31], v[26:27]
	v_pk_add_f32 v[24:25], v[28:29], v[24:25]
	v_pk_add_f32 v[16:17], v[20:21], v[16:17]
	v_pk_add_f32 v[18:19], v[22:23], v[18:19]
	v_pk_add_f32 v[16:17], v[24:25], v[16:17]
	v_pk_add_f32 v[18:19], v[26:27], v[18:19]
	v_add_f32_e32 v16, v16, v17
	v_add_f32_e32 v17, v18, v19
	v_add_f32_e32 v16, v16, v17
	v_fmamk_f32 v16, v16, 0x3a800000, v100
	v_rsq_f32_e32 v20, v16
	v_ashrrev_i32_e32 v77, 31, v76
	v_lshlrev_b64 v[16:17], 12, v[76:77]
	v_lshl_add_u64 v[22:23], v[68:69], 0, v[16:17]
	v_lshlrev_b32_e32 v16, 16, v78
	v_and_b32_e32 v17, 0xffff0000, v78
	v_lshlrev_b32_e32 v18, 16, v79
	v_and_b32_e32 v19, 0xffff0000, v79
	v_pk_mul_f32 v[16:17], v[20:21], v[16:17] op_sel_hi:[0,1]
	v_pk_mul_f32 v[18:19], v[20:21], v[18:19] op_sel_hi:[0,1]
	v_pk_mul_f32 v[18:19], v[2:3], v[18:19]
	v_pk_mul_f32 v[16:17], v[0:1], v[16:17]
	global_store_dwordx4 v[22:23], v[16:19], off sc1 nt
	s_nop 1
	v_lshlrev_b32_e32 v16, 16, v74
	v_and_b32_e32 v17, 0xffff0000, v74
	v_lshlrev_b32_e32 v18, 16, v75
	v_and_b32_e32 v19, 0xffff0000, v75
	v_pk_mul_f32 v[16:17], v[20:21], v[16:17] op_sel_hi:[0,1]
	v_pk_mul_f32 v[18:19], v[20:21], v[18:19] op_sel_hi:[0,1]
	v_pk_mul_f32 v[18:19], v[6:7], v[18:19]
	v_pk_mul_f32 v[16:17], v[4:5], v[16:17]
	global_store_dwordx4 v[22:23], v[16:19], off offset:1024 sc1 nt
	s_nop 1
	v_lshlrev_b32_e32 v16, 16, v72
	v_and_b32_e32 v17, 0xffff0000, v72
	v_lshlrev_b32_e32 v18, 16, v73
	v_and_b32_e32 v19, 0xffff0000, v73
	v_pk_mul_f32 v[16:17], v[20:21], v[16:17] op_sel_hi:[0,1]
	v_pk_mul_f32 v[18:19], v[20:21], v[18:19] op_sel_hi:[0,1]
	v_pk_mul_f32 v[18:19], v[10:11], v[18:19]
	v_pk_mul_f32 v[16:17], v[8:9], v[16:17]
	global_store_dwordx4 v[22:23], v[16:19], off offset:2048 sc1 nt
	s_nop 1
	v_lshlrev_b32_e32 v16, 16, v70
	v_and_b32_e32 v17, 0xffff0000, v70
	v_lshlrev_b32_e32 v18, 16, v71
	v_and_b32_e32 v19, 0xffff0000, v71
	v_pk_mul_f32 v[16:17], v[20:21], v[16:17] op_sel_hi:[0,1]
	v_pk_mul_f32 v[18:19], v[20:21], v[18:19] op_sel_hi:[0,1]
	v_pk_mul_f32 v[18:19], v[14:15], v[18:19]
	v_pk_mul_f32 v[16:17], v[12:13], v[16:17]
	global_store_dwordx4 v[22:23], v[16:19], off offset:3072 sc1 nt
	s_branch .LBB0_625
